# while waiting in the barriers before QKV0, GU0, D0, WO1 and D1, the non-polling waves touch the first two K-steps of the workgroup's first weight tile (L2 warm-up for the GEMM prologue)
# baseline (speedup 1.0000x reference)
.LBB0_124:
	s_or_b64 exec, exec, s[4:5]
	s_waitcnt vmcnt(0)
	s_barrier
	v_readlane_b32 s99, v219, 25
	s_nop 1
	s_cmp_lg_u32 s99, 0
	s_cbranch_scc1 .Lbpf2_skip
	v_readlane_b32 s98, v219, 30
	s_nop 1
	s_lshr_b32 s98, s98, 5
	s_mul_i32 s98, s98, 0x40000
	s_add_u32 s100, s56, s98
	s_addc_u32 s101, s57, 0
	s_add_u32 s100, s100, 0x100000
	s_addc_u32 s101, s101, 0
	v_mbcnt_lo_u32_b32 v221, -1, 0
	v_mbcnt_hi_u32_b32 v221, -1, v221
	v_mul_u32_u24_e32 v221, 0x800, v221
	global_load_dword v223, v221, s[100:101]
	global_load_dword v223, v221, s[100:101] offset:128
	s_add_u32 s100, s100, 0x20000
	s_addc_u32 s101, s101, 0
	global_load_dword v223, v221, s[100:101]
	global_load_dword v223, v221, s[100:101] offset:128
.Lbpf2_skip:
	s_mov_b64 s[4:5], exec
	v_readlane_b32 s0, v219, 25
	v_readlane_b32 s1, v219, 26
	s_and_b64 s[0:1], s[4:5], s[0:1]
	s_mov_b64 exec, s[0:1]
	s_cbranch_execz .LBB0_176
	v_readlane_b32 s0, v219, 27
	v_readlane_b32 s1, v219, 28
	v_readlane_b32 s2, v219, 30
	s_waitcnt vmcnt(0) lgkmcnt(0)
	buffer_inv sc1
	s_and_b32 s3, s2, 31
	s_lshl_b32 s3, s3, 7
	s_add_i32 s3, s3, 64
	v_mov_b32_e32 v1, s3
	v_mov_b32_e32 v0, 1
	s_nop 1
	global_atomic_add v1, v0, s[0:1]
	s_mov_b32 s15, 0

.LBB0_577:
	s_or_b64 exec, exec, s[4:5]
	s_waitcnt vmcnt(0)
	s_barrier
	v_readlane_b32 s99, v219, 25
	s_nop 1
	s_cmp_lg_u32 s99, 0
	s_cbranch_scc1 .Lbpf6_skip
	v_readlane_b32 s98, v219, 30
	s_nop 1
	s_lshr_b32 s98, s98, 5
	s_mul_i32 s98, s98, 0x40000
	s_add_u32 s100, s56, s98
	s_addc_u32 s101, s57, 0
	s_add_u32 s100, s100, 0x900000
	s_addc_u32 s101, s101, 0
	v_mbcnt_lo_u32_b32 v221, -1, 0
	v_mbcnt_hi_u32_b32 v221, -1, v221
	v_mul_u32_u24_e32 v221, 0x800, v221
	global_load_dword v223, v221, s[100:101]
	global_load_dword v223, v221, s[100:101] offset:128
	s_add_u32 s100, s100, 0x20000
	s_addc_u32 s101, s101, 0
	global_load_dword v223, v221, s[100:101]
	global_load_dword v223, v221, s[100:101] offset:128

.Lgu0h_skip:
	s_waitcnt vmcnt(0)
	s_waitcnt vmcnt(0) lgkmcnt(0)
	s_barrier
	v_readlane_b32 s99, v219, 25
	s_nop 1
	s_cmp_lg_u32 s99, 0
	s_cbranch_scc1 .Lbpf7_skip
	v_readlane_b32 s98, v219, 30
	s_nop 1
	s_lshr_b32 s98, s98, 5
	s_mul_i32 s98, s98, 0xb0000
	s_add_u32 s100, s56, s98
	s_addc_u32 s101, s57, 0
	s_add_u32 s100, s100, 0x1400000
	s_addc_u32 s101, s101, 0
	v_mbcnt_lo_u32_b32 v221, -1, 0
	v_mbcnt_hi_u32_b32 v221, -1, v221
	v_mul_u32_u24_e32 v221, 0x1600, v221
	global_load_dword v223, v221, s[100:101]
	global_load_dword v223, v221, s[100:101] offset:128
	s_add_u32 s100, s100, 0x58000
	s_addc_u32 s101, s101, 0
	global_load_dword v223, v221, s[100:101]
	global_load_dword v223, v221, s[100:101] offset:128

.LBB0_1120:
	s_waitcnt vmcnt(0)
	s_barrier
	v_readlane_b32 s99, v219, 25
	s_nop 1
	s_cmp_lg_u32 s99, 0
	s_cbranch_scc1 .Lbpf11_skip
	v_readlane_b32 s98, v219, 30
	s_nop 1
	s_lshr_b32 s98, s98, 5
	s_mul_i32 s98, s98, 0x40000
	s_add_u32 s100, s56, s98
	s_addc_u32 s101, s57, 0
	s_add_u32 s100, s100, 0x1c80000
	s_addc_u32 s101, s101, 0
	v_mbcnt_lo_u32_b32 v221, -1, 0
	v_mbcnt_hi_u32_b32 v221, -1, v221
	v_mul_u32_u24_e32 v221, 0x800, v221
	global_load_dword v223, v221, s[100:101]
	global_load_dword v223, v221, s[100:101] offset:128
	s_add_u32 s100, s100, 0x20000
	s_addc_u32 s101, s101, 0
	global_load_dword v223, v221, s[100:101]
	global_load_dword v223, v221, s[100:101] offset:128
.Lbpf11_skip:
	s_mov_b64 s[6:7], exec
	v_readlane_b32 s0, v219, 25
	v_readlane_b32 s1, v219, 26
	s_and_b64 s[0:1], s[6:7], s[0:1]
	s_mov_b64 exec, s[0:1]
	s_cbranch_execz .LBB0_1172
	v_readlane_b32 s0, v219, 27
	v_readlane_b32 s1, v219, 28
	v_readlane_b32 s2, v219, 30
	s_waitcnt vmcnt(0) lgkmcnt(0)
	buffer_inv sc1
	s_bfe_u32 s3, s2, 0x10002
	s_lshl_b32 s3, s3, 3
	s_bfe_u32 s10, s2, 0x30004
	s_add_i32 s3, s3, s10
	s_add_i32 s3, s3, 16
	s_lshl_b32 s3, s3, 7
	s_add_i32 s3, s3, 0x60
	s_lshr_b32 s10, s2, 4
	s_lshl_b32 s10, s10, 7
	s_add_i32 s10, s10, 0x60
	s_and_b32 s11, s2, 31
	s_lshl_b32 s11, s11, 7
	s_add_i32 s11, s11, 0x60
	v_mov_b32_e32 v0, 1
	v_mov_b32_e32 v1, s3
	v_mov_b32_e32 v2, s10
	s_nop 1
	global_atomic_add v1, v0, s[0:1]
	global_atomic_add v2, v0, s[0:1]
	v_mov_b32_e32 v2, 0x1140
	s_nop 1
	global_atomic_add v2, v0, s[0:1]
	v_mov_b32_e32 v1, s11
	s_mov_b32 s15, 0

.LBB0_1409:
	s_waitcnt vmcnt(0)
	s_waitcnt vmcnt(0) lgkmcnt(0)
	s_barrier
	v_readlane_b32 s99, v219, 25
	s_nop 1
	s_cmp_lg_u32 s99, 0
	s_cbranch_scc1 .Lbpf14_skip
	v_readlane_b32 s98, v219, 30
	s_nop 1
	s_lshr_b32 s98, s98, 5
	s_mul_i32 s98, s98, 0xb0000
	s_add_u32 s100, s56, s98
	s_addc_u32 s101, s57, 0
	s_add_u32 s100, s100, 0x2980000
	s_addc_u32 s101, s101, 0
	v_mbcnt_lo_u32_b32 v221, -1, 0
	v_mbcnt_hi_u32_b32 v221, -1, v221
	v_mul_u32_u24_e32 v221, 0x1600, v221
	global_load_dword v223, v221, s[100:101]
	global_load_dword v223, v221, s[100:101] offset:128
	s_add_u32 s100, s100, 0x58000
	s_addc_u32 s101, s101, 0
	global_load_dword v223, v221, s[100:101]
	global_load_dword v223, v221, s[100:101] offset:128
.Lbpf14_skip:
	s_mov_b64 s[6:7], exec
	v_readlane_b32 s0, v219, 25
	v_readlane_b32 s1, v219, 26
	s_and_b64 s[0:1], s[6:7], s[0:1]
	s_mov_b64 exec, s[0:1]
	s_cbranch_execz .LBB0_1461
	v_readlane_b32 s0, v219, 27
	v_readlane_b32 s1, v219, 28
	v_readlane_b32 s2, v219, 30
	s_waitcnt vmcnt(0) lgkmcnt(0)
	buffer_inv sc1
	s_and_b32 s3, s2, 31
	s_lshl_b32 s3, s3, 7
	s_add_i32 s3, s3, 64
	v_mov_b32_e32 v1, s3
	v_mov_b32_e32 v0, 1
	s_nop 1
	global_atomic_add v1, v0, s[0:1]
	s_mov_b32 s15, 0
